# as v44 plus attention main loop: no m0 save/restore around the LDS-DMA issues
# speedup vs baseline: 1.0061x; 1.0011x over previous
; __device__ __forceinline__ void glds16(const void*gsrc,unsigned lds_dst){unsigned keep;
;   asm volatile("s_mov_b32 %0, m0\n\ts_mov_b32 m0, %2\n\ts_nop 0\n\tglobal_load_lds_dwordx4 %1, off\n\ts_mov_b32 m0, %0":"=&s"(keep):"v"(gsrc),"s"(lds_dst):"memory");}
.LBB0_295:
	v_add_u32_e32 v184, s0, v253
	ds_read_b64_tr_b16 v[176:177], v184 offset:24576
	ds_read_b64_tr_b16 v[178:179], v184 offset:25088
	s_waitcnt lgkmcnt(9)
	v_mfma_f32_32x32x16_bf16 v[96:111], v[172:175], v[116:119], v[32:47]
	v_add_f32_e32 v80, v64, v65
	v_add_f32_e32 v80, v66, v80
	v_add_f32_e32 v80, v67, v80
	v_add_f32_e32 v80, v68, v80
	v_add_f32_e32 v80, v69, v80
	v_cvt_pk_bf16_f32 v140, v64, v65
	v_cvt_pk_bf16_f32 v141, v66, v67
	ds_read_b64_tr_b16 v[172:173], v184 offset:28672
	ds_read_b64_tr_b16 v[174:175], v184 offset:29184
	v_add_f32_e32 v64, v70, v80
	s_waitcnt lgkmcnt(10)
	v_mfma_f32_32x32x16_bf16 v[80:95], v[168:171], v[116:119], v[32:47]
	v_add_f32_e32 v64, v71, v64
	v_add_f32_e32 v64, v72, v64
	v_add_f32_e32 v124, v73, v64
	v_cvt_pk_bf16_f32 v142, v68, v69
	v_cvt_pk_bf16_f32 v143, v70, v71
	ds_read_b64_tr_b16 v[64:65], v184 offset:25600
	ds_read_b64_tr_b16 v[66:67], v184 offset:26112
	s_waitcnt lgkmcnt(11)
	v_mfma_f32_32x32x16_bf16 v[96:111], v[164:167], v[112:115], v[96:111]
	v_add_f32_e32 v68, v74, v124
	v_add_f32_e32 v68, v75, v68
	v_add_f32_e32 v68, v76, v68
	v_add_f32_e32 v124, v77, v68
	v_cvt_pk_bf16_f32 v136, v72, v73
	v_cvt_pk_bf16_f32 v137, v74, v75
	ds_read_b64_tr_b16 v[68:69], v184 offset:29696
	ds_read_b64_tr_b16 v[70:71], v184 offset:30208
	s_waitcnt lgkmcnt(12)
	v_mfma_f32_32x32x16_bf16 v[80:95], v[160:163], v[112:115], v[80:95]
	v_add_f32_e32 v72, v78, v124
	v_add_f32_e32 v72, v79, v72
	v_add_f32_e32 v72, v48, v72
	v_add_f32_e32 v124, v49, v72
	v_cvt_pk_bf16_f32 v138, v76, v77
	v_cvt_pk_bf16_f32 v139, v78, v79
	ds_read_b64_tr_b16 v[72:73], v184 offset:26624
	ds_read_b64_tr_b16 v[74:75], v184 offset:27136
	s_waitcnt lgkmcnt(13)
	v_mfma_f32_32x32x16_bf16 v[96:111], v[156:159], v[120:123], v[96:111]
	v_add_f32_e32 v76, v50, v124
	v_add_f32_e32 v76, v51, v76
	v_add_f32_e32 v76, v52, v76
	v_add_f32_e32 v76, v53, v76
	v_cvt_pk_bf16_f32 v128, v48, v49
	v_cvt_pk_bf16_f32 v129, v50, v51
	ds_read_b64_tr_b16 v[48:49], v184 offset:30720
	ds_read_b64_tr_b16 v[50:51], v184 offset:31232
	s_waitcnt lgkmcnt(14)
	v_mfma_f32_32x32x16_bf16 v[80:95], v[152:155], v[120:123], v[80:95]
	v_add_f32_e32 v76, v54, v76
	v_add_f32_e32 v76, v55, v76
	v_add_f32_e32 v76, v56, v76
	v_add_f32_e32 v76, v57, v76
	v_cvt_pk_bf16_f32 v130, v52, v53
	v_cvt_pk_bf16_f32 v131, v54, v55
	ds_read_b64_tr_b16 v[52:53], v184 offset:27648
	ds_read_b64_tr_b16 v[54:55], v184 offset:28160
	s_waitcnt lgkmcnt(14)
	v_mfma_f32_32x32x16_bf16 v[96:111], v[148:151], v[132:135], v[96:111]
	v_add_f32_e32 v76, v58, v76
	v_add_f32_e32 v76, v59, v76
	v_add_f32_e32 v76, v60, v76
	v_add_f32_e32 v76, v61, v76
	v_cvt_pk_bf16_f32 v124, v56, v57
	v_cvt_pk_bf16_f32 v125, v58, v59
	ds_read_b64_tr_b16 v[56:57], v184 offset:31744
	ds_read_b64_tr_b16 v[58:59], v184 offset:32256
	v_mfma_f32_32x32x16_bf16 v[80:95], v[144:147], v[132:135], v[80:95]
	v_add_f32_e32 v76, v62, v76
	v_add_f32_e32 v76, v63, v76
	v_add_f32_e32 v76, 0, v76
	v_cvt_pk_bf16_f32 v126, v60, v61
	v_cvt_pk_bf16_f32 v127, v62, v63
	v_lshl_add_u64 v[60:61], v[182:183], 0, s[8:9]
	s_add_i32 s0, s43, s68
	s_mov_b32 m0, s0
	s_nop 0
	global_load_lds_dwordx4 v[60:61], off
	v_lshl_add_u64 v[60:61], v[180:181], 0, s[8:9]
	s_add_i32 s0, s38, s69
	s_mov_b32 m0, s0
	s_nop 0
	global_load_lds_dwordx4 v[60:61], off
	v_max_f32_e32 v60, v96, v97


	v_max3_f32 v61, v98, v99, v81
	v_max3_f32 v60, v60, v80, v82
	v_max3_f32 v60, v60, v83, v100
	v_max3_f32 v61, v61, v102, v103
	v_max3_f32 v60, v60, v101, v84
	v_max3_f32 v61, v61, v86, v87
	v_max3_f32 v60, v60, v85, v104
	v_max3_f32 v61, v61, v106, v107
	v_max3_f32 v60, v60, v105, v88
	v_max3_f32 v61, v61, v90, v91
	v_max3_f32 v60, v60, v89, v108
	v_max3_f32 v61, v61, v110, v111
	v_max3_f32 v60, v60, v109, v92
	v_max3_f32 v61, v61, v94, v95
	v_max3_f32 v60, v60, v93, v61
	v_mov_b32_e32 v61, v60
	s_nop 1
	v_permlane32_swap_b32_e32 v60, v61


	v_max_f32_e32 v60, v60, v61
	v_cmp_lt_f32_e32 vcc, s84, v60
	s_cmp_lg_u64 vcc, 0
	v_add_f32_e32 v184, v237, v76
	s_cselect_b64 s[36:37], -1, 0
	s_cbranch_vccnz .LBB0_303

.LBB0_298:
	ds_read_b64_tr_b16 v[148:149], v185 offset:24576
	ds_read_b64_tr_b16 v[150:151], v185 offset:25088
	s_waitcnt lgkmcnt(9)
	v_mfma_f32_32x32x16_bf16 v[64:79], v[60:63], v[116:119], v[32:47]
	v_add_f32_e32 v48, v96, v97
	v_add_f32_e32 v48, v98, v48
	v_add_f32_e32 v48, v99, v48
	v_add_f32_e32 v48, v100, v48
	v_add_f32_e32 v48, v101, v48
	v_cvt_pk_bf16_f32 v140, v96, v97
	v_cvt_pk_bf16_f32 v141, v98, v99
	ds_read_b64_tr_b16 v[144:145], v185 offset:28672
	ds_read_b64_tr_b16 v[146:147], v185 offset:29184
	v_add_f32_e32 v48, v102, v48
	v_add_f32_e32 v48, v103, v48
	v_add_f32_e32 v48, v104, v48
	v_add_f32_e32 v124, v105, v48
	s_waitcnt lgkmcnt(10)
	v_mfma_f32_32x32x16_bf16 v[48:63], v[172:175], v[116:119], v[32:47]
	v_cvt_pk_bf16_f32 v142, v100, v101
	v_cvt_pk_bf16_f32 v143, v102, v103
	ds_read_b64_tr_b16 v[96:97], v185 offset:25600
	ds_read_b64_tr_b16 v[98:99], v185 offset:26112
	s_waitcnt lgkmcnt(11)
	v_mfma_f32_32x32x16_bf16 v[64:79], v[176:179], v[112:115], v[64:79]
	v_add_f32_e32 v100, v106, v124
	v_add_f32_e32 v100, v107, v100
	v_add_f32_e32 v100, v108, v100
	v_add_f32_e32 v124, v109, v100
	v_cvt_pk_bf16_f32 v136, v104, v105
	v_cvt_pk_bf16_f32 v137, v106, v107
	ds_read_b64_tr_b16 v[100:101], v185 offset:29696
	ds_read_b64_tr_b16 v[102:103], v185 offset:30208
	s_waitcnt lgkmcnt(12)
	v_mfma_f32_32x32x16_bf16 v[48:63], v[168:171], v[112:115], v[48:63]
	v_add_f32_e32 v104, v110, v124
	v_add_f32_e32 v104, v111, v104
	v_add_f32_e32 v104, v80, v104
	v_add_f32_e32 v124, v81, v104
	v_cvt_pk_bf16_f32 v138, v108, v109
	v_cvt_pk_bf16_f32 v139, v110, v111
	ds_read_b64_tr_b16 v[104:105], v185 offset:26624
	ds_read_b64_tr_b16 v[106:107], v185 offset:27136
	s_waitcnt lgkmcnt(13)
	v_mfma_f32_32x32x16_bf16 v[64:79], v[164:167], v[120:123], v[64:79]
	v_add_f32_e32 v108, v82, v124
	v_add_f32_e32 v108, v83, v108
	v_add_f32_e32 v108, v84, v108
	v_add_f32_e32 v108, v85, v108
	v_cvt_pk_bf16_f32 v128, v80, v81
	v_cvt_pk_bf16_f32 v129, v82, v83
	ds_read_b64_tr_b16 v[80:81], v185 offset:30720
	ds_read_b64_tr_b16 v[82:83], v185 offset:31232
	s_waitcnt lgkmcnt(14)
	v_mfma_f32_32x32x16_bf16 v[48:63], v[160:163], v[120:123], v[48:63]
	v_add_f32_e32 v108, v86, v108
	v_add_f32_e32 v108, v87, v108
	v_add_f32_e32 v108, v88, v108
	v_add_f32_e32 v108, v89, v108
	v_cvt_pk_bf16_f32 v130, v84, v85
	v_cvt_pk_bf16_f32 v131, v86, v87
	ds_read_b64_tr_b16 v[84:85], v185 offset:27648
	ds_read_b64_tr_b16 v[86:87], v185 offset:28160
	s_waitcnt lgkmcnt(14)
	v_mfma_f32_32x32x16_bf16 v[64:79], v[156:159], v[132:135], v[64:79]
	v_add_f32_e32 v108, v90, v108
	v_add_f32_e32 v108, v91, v108
	v_add_f32_e32 v108, v92, v108
	v_add_f32_e32 v108, v93, v108
	v_cvt_pk_bf16_f32 v124, v88, v89
	v_cvt_pk_bf16_f32 v125, v90, v91
	ds_read_b64_tr_b16 v[88:89], v185 offset:31744
	ds_read_b64_tr_b16 v[90:91], v185 offset:32256
	v_mfma_f32_32x32x16_bf16 v[48:63], v[152:155], v[132:135], v[48:63]
	v_add_f32_e32 v108, v94, v108
	v_add_f32_e32 v108, v95, v108
	v_add_f32_e32 v108, 0, v108
	v_cvt_pk_bf16_f32 v126, v92, v93
	v_cvt_pk_bf16_f32 v127, v94, v95
	v_max_f32_e32 v92, v64, v65


	s_nop 6
	v_max3_f32 v93, v66, v67, v49
	v_max3_f32 v92, v92, v48, v50
	v_max3_f32 v92, v92, v51, v68
	v_max3_f32 v93, v93, v70, v71
	v_max3_f32 v92, v92, v69, v52
	v_max3_f32 v93, v93, v54, v55
	v_max3_f32 v92, v92, v53, v72
	v_max3_f32 v93, v93, v74, v75
	v_max3_f32 v92, v92, v73, v56
	v_max3_f32 v93, v93, v58, v59
	v_max3_f32 v92, v92, v57, v76
	v_max3_f32 v93, v93, v78, v79
	v_max3_f32 v92, v92, v77, v60
	v_max3_f32 v93, v93, v62, v63
	v_max3_f32 v92, v92, v61, v93
	v_mov_b32_e32 v93, v92
	s_nop 1
	v_permlane32_swap_b32_e32 v92, v93


; __device__ __forceinline__ void glds16(const void*gsrc,unsigned lds_dst){unsigned keep;
;   asm volatile("s_mov_b32 %0, m0\n\ts_mov_b32 m0, %2\n\ts_nop 0\n\tglobal_load_lds_dwordx4 %1, off\n\ts_mov_b32 m0, %0":"=&s"(keep):"v"(gsrc),"s"(lds_dst):"memory");}
	s_add_i32 s0, s38, s68
	s_mov_b32 m0, s0
	s_nop 0
	global_load_lds_dwordx4 v[182:183], off
	v_max_f32_e32 v92, v92, v93
	s_add_i32 s0, s71, s69
	s_mov_b32 m0, s0
	s_nop 0
	global_load_lds_dwordx4 v[180:181], off
	v_cmp_lt_f32_e32 vcc, s84, v92
	s_cmp_lg_u64 vcc, 0
	v_add_f32_e32 v237, v184, v108
	s_cselect_b64 s[36:37], -1, 0
	s_cbranch_vccnz .LBB0_306
